# phase 0: nt hint also on the bf16 weight-copy stores
# baseline (speedup 1.0000x reference)
.LBB0_22:
	s_waitcnt vmcnt(16)
	s_waitcnt vmcnt(0)
	ds_write2_b32 v31, v27, v44 offset1:66
	ds_write2_b32 v31, v45, v46 offset0:132 offset1:198
	ds_write2_b32 v37, v47, v48 offset0:8 offset1:74
	ds_write2_b32 v37, v49, v50 offset0:140 offset1:206
	ds_write2_b32 v38, v51, v52 offset0:16 offset1:82
	ds_write2_b32 v38, v53, v54 offset0:148 offset1:214
	ds_write2_b32 v39, v55, v56 offset0:24 offset1:90
	ds_write2_b32 v39, v57, v58 offset0:156 offset1:222
	ds_write2_b32 v40, v59, v60 offset0:32 offset1:98
	ds_write2_b32 v40, v61, v62 offset0:164 offset1:230
	ds_write2_b32 v41, v63, v64 offset0:40 offset1:106
	ds_write2_b32 v41, v65, v66 offset0:172 offset1:238
	ds_write2_b32 v42, v67, v68 offset0:48 offset1:114
	ds_write2_b32 v42, v69, v70 offset0:180 offset1:246
	ds_write2_b32 v43, v71, v72 offset0:56 offset1:122
	ds_write2_b32 v43, v73, v74 offset0:188 offset1:254
	s_waitcnt lgkmcnt(0)
	ds_read2_b32 v[48:49], v33 offset1:8
	ds_read2_b32 v[50:51], v33 offset0:33 offset1:41
	ds_read2_b32 v[54:55], v33 offset0:66 offset1:74
	ds_read2_b32 v[56:57], v33 offset0:99 offset1:107
	ds_read2_b32 v[58:59], v33 offset0:132 offset1:140
	ds_read2_b32 v[60:61], v33 offset0:165 offset1:173
	ds_read2_b32 v[62:63], v33 offset0:198 offset1:206
	ds_read2_b32 v[64:65], v33 offset0:231 offset1:239
	s_waitcnt lgkmcnt(7)
	v_mov_b32_e32 v44, v48
	s_waitcnt lgkmcnt(6)
	v_mov_b32_e32 v45, v50
	s_waitcnt lgkmcnt(5)
	v_mov_b32_e32 v46, v54
	s_waitcnt lgkmcnt(4)
	v_mov_b32_e32 v47, v56
	v_pk_mul_f32 v[44:45], v[4:5], v[44:45]
	v_pk_mul_f32 v[46:47], v[6:7], v[46:47]
	v_cvt_pk_bf16_f32 v44, v44, v45
	v_cvt_pk_bf16_f32 v45, v46, v47
	s_waitcnt lgkmcnt(3)
	v_mov_b32_e32 v46, v58
	s_waitcnt lgkmcnt(2)
	v_mov_b32_e32 v47, v60
	s_waitcnt lgkmcnt(1)
	v_mov_b32_e32 v66, v62
	s_waitcnt lgkmcnt(0)
	v_mov_b32_e32 v67, v64
	v_pk_mul_f32 v[46:47], v[0:1], v[46:47]
	v_pk_mul_f32 v[66:67], v[2:3], v[66:67]
	v_cvt_pk_bf16_f32 v46, v46, v47
	v_cvt_pk_bf16_f32 v47, v66, v67
	v_add_u32_e32 v66, s16, v32
	v_ashrrev_i32_e32 v67, 31, v66
	v_lshl_add_u64 v[52:53], s[26:27], 1, v[20:21]
	v_lshlrev_b64 v[68:69], 11, v[66:67]
	v_lshl_add_u64 v[68:69], v[52:53], 0, v[68:69]
	v_mov_b32_e32 v50, v49
	v_mov_b32_e32 v56, v55
	global_store_dwordx4 v[68:69], v[44:47], off nt
	v_mov_b32_e32 v60, v59
	v_mov_b32_e32 v64, v63
	v_pk_mul_f32 v[44:45], v[4:5], v[50:51]
	v_pk_mul_f32 v[46:47], v[6:7], v[56:57]
	v_cvt_pk_bf16_f32 v44, v44, v45
	v_cvt_pk_bf16_f32 v45, v46, v47
	v_pk_mul_f32 v[46:47], v[0:1], v[60:61]
	v_pk_mul_f32 v[48:49], v[2:3], v[64:65]
	v_cvt_pk_bf16_f32 v46, v46, v47
	v_cvt_pk_bf16_f32 v47, v48, v49
	v_add_u32_e32 v48, 8, v66
	v_ashrrev_i32_e32 v49, 31, v48
	v_lshlrev_b64 v[48:49], 11, v[48:49]
	v_lshl_add_u64 v[48:49], v[52:53], 0, v[48:49]
	ds_read2_b32 v[50:51], v33 offset0:16 offset1:24
	ds_read2_b32 v[54:55], v33 offset0:49 offset1:57
	global_store_dwordx4 v[48:49], v[44:47], off nt
	ds_read2_b32 v[48:49], v33 offset0:82 offset1:90
	ds_read2_b32 v[56:57], v33 offset0:115 offset1:123
	ds_read2_b32 v[58:59], v33 offset0:148 offset1:156
	ds_read2_b32 v[60:61], v33 offset0:181 offset1:189
	ds_read2_b32 v[62:63], v33 offset0:214 offset1:222
	ds_read2_b32 v[64:65], v33 offset0:247 offset1:255
	s_waitcnt lgkmcnt(7)
	v_mov_b32_e32 v44, v50
	s_waitcnt lgkmcnt(6)
	v_mov_b32_e32 v45, v54
	s_waitcnt lgkmcnt(5)
	v_mov_b32_e32 v46, v48
	s_waitcnt lgkmcnt(4)
	v_mov_b32_e32 v47, v56
	v_pk_mul_f32 v[44:45], v[4:5], v[44:45]
	v_pk_mul_f32 v[46:47], v[6:7], v[46:47]
	v_cvt_pk_bf16_f32 v44, v44, v45
	v_cvt_pk_bf16_f32 v45, v46, v47
	s_waitcnt lgkmcnt(3)
	v_mov_b32_e32 v46, v58
	s_waitcnt lgkmcnt(2)
	v_mov_b32_e32 v47, v60
	v_mov_b32_e32 v54, v51
	v_mov_b32_e32 v56, v49
	v_mov_b32_e32 v60, v59
	v_pk_mul_f32 v[46:47], v[0:1], v[46:47]
	s_waitcnt lgkmcnt(1)
	v_mov_b32_e32 v68, v62
	s_waitcnt lgkmcnt(0)
	v_mov_b32_e32 v69, v64
	v_pk_mul_f32 v[4:5], v[4:5], v[54:55]
	v_pk_mul_f32 v[6:7], v[6:7], v[56:57]
	v_pk_mul_f32 v[0:1], v[0:1], v[60:61]
	v_mov_b32_e32 v64, v63
	v_pk_mul_f32 v[68:69], v[2:3], v[68:69]
	v_cvt_pk_bf16_f32 v4, v4, v5
	v_cvt_pk_bf16_f32 v5, v6, v7
	v_cvt_pk_bf16_f32 v6, v0, v1
	v_pk_mul_f32 v[0:1], v[2:3], v[64:65]
	v_cvt_pk_bf16_f32 v46, v46, v47
	v_cvt_pk_bf16_f32 v47, v68, v69
	v_add_u32_e32 v68, 16, v66
	v_cvt_pk_bf16_f32 v7, v0, v1
	v_add_u32_e32 v0, 24, v66
	v_ashrrev_i32_e32 v69, 31, v68
	v_ashrrev_i32_e32 v1, 31, v0
	v_lshlrev_b64 v[68:69], 11, v[68:69]
	v_lshlrev_b64 v[0:1], 11, v[0:1]
	v_lshl_add_u64 v[68:69], v[52:53], 0, v[68:69]
	v_lshl_add_u64 v[0:1], v[52:53], 0, v[0:1]
	global_store_dwordx4 v[68:69], v[44:47], off nt
	global_store_dwordx4 v[0:1], v[4:7], off nt
	s_waitcnt lgkmcnt(0)
	v_readlane_b32 s72, v254, 10

.LBB0_24:
	s_cmpk_gt_i32 s90, 0x11ff
	s_mov_b64 s[16:17], -1
	s_cbranch_scc0 .LBB0_59
	s_cmpk_gt_u32 s90, 0x13ff
	s_cbranch_scc0 .LBB0_56
	s_cmpk_gt_u32 s90, 0x17ff
	s_cbranch_scc0 .LBB0_50
	s_cmpk_gt_u32 s90, 0x19ff
	s_cbranch_scc0 .LBB0_44
	s_cmpk_gt_u32 s90, 0x1bff
	s_cbranch_scc0 .LBB0_41
	s_cmpk_gt_u32 s90, 0x31ff
	s_cbranch_scc0 .LBB0_31
	s_add_i32 s6, s90, 0xffffce00
	s_add_i32 s16, s90, 0xffffc880
	s_cmpk_lt_u32 s6, 0x580
	s_cselect_b32 s16, s6, s16
	s_cmpk_gt_u32 s6, 0x57f
	s_cselect_b32 s6, 0xb00000, 0
	s_cselect_b32 s26, 0x580000, 0
	s_add_u32 s72, s24, s6
	s_addc_u32 s73, s25, 0
	s_lshl_b32 s6, s16, 1
	s_and_b32 s17, s6, 0xfc0
	s_lshl_b32 s6, s16, 5
	s_and_b32 s16, s6, 0x3e0
	v_or_b32_e32 v0, s17, v30
	s_add_u32 s26, s34, s26
	v_lshlrev_b32_e32 v0, 12, v0
	v_mov_b32_e32 v1, v9
	s_addc_u32 s27, s35, 0
	v_lshl_add_u64 v[0:1], s[72:73], 0, v[0:1]
	s_lshl_b32 s6, s16, 2
	v_lshl_add_u64 v[0:1], v[0:1], 0, s[6:7]
	v_lshl_add_u64 v[0:1], v[0:1], 0, v[8:9]
	s_movk_i32 s6, 0x2000
	v_add_co_u32_e32 v2, vcc, s6, v0
	s_movk_i32 s6, 0x4000
	s_nop 0
	v_addc_co_u32_e32 v3, vcc, 0, v1, vcc
	v_add_co_u32_e32 v4, vcc, s6, v0
	s_movk_i32 s6, 0x6000
	s_nop 0
	v_addc_co_u32_e32 v5, vcc, 0, v1, vcc
	v_add_co_u32_e32 v6, vcc, s6, v0
	s_mov_b32 s6, 0x8000
	s_nop 0
	v_addc_co_u32_e32 v7, vcc, 0, v1, vcc
	v_add_co_u32_e32 v44, vcc, s6, v0
	s_mov_b32 s6, 0xa000
	s_nop 0
	v_addc_co_u32_e32 v45, vcc, 0, v1, vcc
	v_add_co_u32_e32 v46, vcc, s6, v0
	s_mov_b32 s6, 0xc000
	s_nop 0
	v_addc_co_u32_e32 v47, vcc, 0, v1, vcc
	v_add_co_u32_e32 v48, vcc, s6, v0
	s_mov_b32 s6, 0xe000
	s_nop 0
	v_addc_co_u32_e32 v49, vcc, 0, v1, vcc
	v_add_co_u32_e32 v50, vcc, s6, v0
	s_mov_b32 s6, 0x10000
	s_nop 0
	v_addc_co_u32_e32 v51, vcc, 0, v1, vcc
	global_load_dword v27, v[0:1], off nt
	global_load_dword v54, v[2:3], off nt
	global_load_dword v55, v[4:5], off nt
	global_load_dword v56, v[6:7], off nt
	global_load_dword v57, v[44:45], off nt
	global_load_dword v58, v[46:47], off nt
	global_load_dword v59, v[48:49], off nt
	global_load_dword v60, v[50:51], off nt
	v_add_co_u32_e32 v2, vcc, s6, v0
	s_mov_b32 s6, 0x14000
	s_nop 0
	v_addc_co_u32_e32 v3, vcc, 0, v1, vcc
	v_add_co_u32_e32 v4, vcc, s42, v0
	v_readlane_b32 s72, v254, 10
	s_nop 0
	v_addc_co_u32_e32 v5, vcc, 0, v1, vcc
	v_add_co_u32_e32 v6, vcc, s6, v0
	s_mov_b32 s6, 0x18000
	s_nop 0
	v_addc_co_u32_e32 v7, vcc, 0, v1, vcc
	v_add_co_u32_e32 v44, vcc, s43, v0
	s_nop 1
	v_addc_co_u32_e32 v45, vcc, 0, v1, vcc
	v_add_co_u32_e32 v46, vcc, s6, v0
	s_mov_b32 s6, 0x1a000
	s_nop 0
	v_addc_co_u32_e32 v47, vcc, 0, v1, vcc
	v_add_co_u32_e32 v48, vcc, s6, v0
	s_mov_b32 s6, 0x1c000
	s_nop 0
	v_addc_co_u32_e32 v49, vcc, 0, v1, vcc
	v_add_co_u32_e32 v50, vcc, s6, v0
	s_mov_b32 s6, 0x1e000
	s_nop 0
	v_addc_co_u32_e32 v51, vcc, 0, v1, vcc
	v_add_co_u32_e32 v52, vcc, s6, v0
	s_mov_b32 s6, 0x20000
	s_nop 0
	v_addc_co_u32_e32 v53, vcc, 0, v1, vcc
	global_load_dword v61, v[2:3], off nt
	global_load_dword v62, v[4:5], off nt
	global_load_dword v63, v[6:7], off nt
	global_load_dword v64, v[44:45], off nt
	global_load_dword v65, v[46:47], off nt
	global_load_dword v66, v[48:49], off nt
	global_load_dword v67, v[50:51], off nt
	global_load_dword v68, v[52:53], off nt
	v_add_co_u32_e32 v2, vcc, s6, v0
	s_mov_b32 s6, 0x22000
	s_nop 0
	v_addc_co_u32_e32 v3, vcc, 0, v1, vcc
	v_add_co_u32_e32 v4, vcc, s6, v0
	s_mov_b32 s6, 0x26000
	s_nop 0
	v_addc_co_u32_e32 v5, vcc, 0, v1, vcc
	v_add_co_u32_e32 v6, vcc, s44, v0
	s_nop 1
	v_addc_co_u32_e32 v7, vcc, 0, v1, vcc
	v_add_co_u32_e32 v44, vcc, s6, v0
	s_mov_b32 s6, 0x28000
	s_nop 0
	v_addc_co_u32_e32 v45, vcc, 0, v1, vcc
	v_add_co_u32_e32 v46, vcc, s6, v0
	s_mov_b32 s6, 0x2a000
	s_nop 0
	v_addc_co_u32_e32 v47, vcc, 0, v1, vcc
	v_add_co_u32_e32 v48, vcc, s6, v0
	s_mov_b32 s6, 0x2e000
	s_nop 0
	v_addc_co_u32_e32 v49, vcc, 0, v1, vcc
	v_add_co_u32_e32 v50, vcc, s45, v0
	s_nop 1
	v_addc_co_u32_e32 v51, vcc, 0, v1, vcc
	v_add_co_u32_e32 v52, vcc, s6, v0
	s_mov_b32 s6, 0x30000
	s_nop 0
	v_addc_co_u32_e32 v53, vcc, 0, v1, vcc
	global_load_dword v69, v[2:3], off nt
	global_load_dword v70, v[4:5], off nt
	global_load_dword v71, v[6:7], off nt
	global_load_dword v72, v[44:45], off nt
	global_load_dword v73, v[46:47], off nt
	global_load_dword v74, v[48:49], off nt
	global_load_dword v75, v[50:51], off nt
	s_nop 0
	global_load_dword v52, v[52:53], off nt
	v_add_co_u32_e32 v2, vcc, s6, v0
	s_mov_b32 s6, 0x32000
	s_nop 0
	v_addc_co_u32_e32 v3, vcc, 0, v1, vcc
	v_add_co_u32_e32 v4, vcc, s6, v0
	s_mov_b32 s6, 0x34000
	s_nop 0
	v_addc_co_u32_e32 v5, vcc, 0, v1, vcc
	v_add_co_u32_e32 v6, vcc, s6, v0
	s_mov_b32 s6, 0x38000
	s_nop 0
	v_addc_co_u32_e32 v7, vcc, 0, v1, vcc
	v_add_co_u32_e32 v44, vcc, s46, v0
	s_nop 1
	v_addc_co_u32_e32 v45, vcc, 0, v1, vcc
	v_add_co_u32_e32 v46, vcc, s6, v0
	s_mov_b32 s6, 0x3a000
	s_nop 0
	v_addc_co_u32_e32 v47, vcc, 0, v1, vcc
	v_add_co_u32_e32 v48, vcc, s6, v0
	s_mov_b32 s6, 0x3c000
	s_nop 0
	v_addc_co_u32_e32 v49, vcc, 0, v1, vcc
	v_add_co_u32_e32 v50, vcc, s6, v0
	s_mov_b32 s6, 0x3e000
	s_nop 0
	v_addc_co_u32_e32 v51, vcc, 0, v1, vcc
	v_add_co_u32_e32 v0, vcc, s6, v0
	s_lshl_b32 s6, s17, 1
	s_nop 0
	v_addc_co_u32_e32 v1, vcc, 0, v1, vcc
	global_load_dword v2, v[2:3], off nt
	s_nop 0
	global_load_dword v3, v[4:5], off nt
	s_nop 0
	global_load_dword v4, v[6:7], off nt
	global_load_dword v5, v[44:45], off nt
	s_nop 0
	global_load_dword v6, v[46:47], off nt
	global_load_dword v7, v[48:49], off nt
	global_load_dword v44, v[50:51], off nt
	s_nop 0
	global_load_dword v0, v[0:1], off nt
	s_waitcnt vmcnt(16)
	s_waitcnt vmcnt(0)
	ds_write2_b32 v31, v27, v54 offset1:66
	ds_write2_b32 v31, v55, v56 offset0:132 offset1:198
	ds_write2_b32 v37, v57, v58 offset0:8 offset1:74
	ds_write2_b32 v37, v59, v60 offset0:140 offset1:206
	ds_write2_b32 v38, v61, v62 offset0:16 offset1:82
	ds_write2_b32 v38, v63, v64 offset0:148 offset1:214
	ds_write2_b32 v39, v65, v66 offset0:24 offset1:90
	ds_write2_b32 v39, v67, v68 offset0:156 offset1:222
	ds_write2_b32 v40, v69, v70 offset0:32 offset1:98
	ds_write2_b32 v40, v71, v72 offset0:164 offset1:230
	ds_write2_b32 v41, v73, v74 offset0:40 offset1:106
	ds_write2_b32 v41, v75, v52 offset0:172 offset1:238
	ds_write2_b32 v42, v2, v3 offset0:48 offset1:114
	ds_write2_b32 v42, v4, v5 offset0:180 offset1:246
	ds_write2_b32 v43, v6, v7 offset0:56 offset1:122
	ds_write2_b32 v43, v44, v0 offset0:188 offset1:254
	s_waitcnt lgkmcnt(0)
	ds_read2_b32 v[4:5], v33 offset0:33 offset1:41
	ds_read2_b32 v[6:7], v33 offset1:8
	ds_read2_b32 v[44:45], v33 offset0:66 offset1:74
	ds_read2_b32 v[46:47], v33 offset0:99 offset1:107
	ds_read2_b32 v[48:49], v33 offset0:132 offset1:140
	ds_read2_b32 v[50:51], v33 offset0:165 offset1:173
	ds_read2_b32 v[52:53], v33 offset0:198 offset1:206
	ds_read2_b32 v[54:55], v33 offset0:231 offset1:239
	s_add_u32 s26, s26, s6
	s_waitcnt lgkmcnt(6)
	v_cvt_pk_bf16_f32 v0, v6, v4
	v_or_b32_e32 v4, s16, v32
	s_addc_u32 s27, s27, 0
	v_mov_b32_e32 v27, v9
	v_mul_u32_u24_e32 v4, 0xb00, v4
	v_lshl_add_u64 v[56:57], s[26:27], 0, v[26:27]
	v_lshlrev_b32_e32 v58, 1, v4
	v_mov_b32_e32 v59, v9
	s_waitcnt lgkmcnt(4)
	v_cvt_pk_bf16_f32 v1, v44, v46
	s_waitcnt lgkmcnt(2)
	v_cvt_pk_bf16_f32 v2, v48, v50
	s_waitcnt lgkmcnt(0)
	v_cvt_pk_bf16_f32 v3, v52, v54
	v_lshl_add_u64 v[58:59], v[56:57], 0, v[58:59]
	v_or_b32_e32 v4, s16, v34
	global_store_dwordx4 v[58:59], v[0:3], off nt
	v_mul_u32_u24_e32 v4, 0xb00, v4
	v_lshlrev_b32_e32 v4, 1, v4
	v_cvt_pk_bf16_f32 v0, v7, v5
	v_cvt_pk_bf16_f32 v1, v45, v47
	v_cvt_pk_bf16_f32 v2, v49, v51
	v_cvt_pk_bf16_f32 v3, v53, v55
	v_mov_b32_e32 v5, v9
	ds_read2_b32 v[6:7], v33 offset0:16 offset1:24
	ds_read2_b32 v[44:45], v33 offset0:49 offset1:57
	ds_read2_b32 v[46:47], v33 offset0:82 offset1:90
	ds_read2_b32 v[48:49], v33 offset0:115 offset1:123
	ds_read2_b32 v[50:51], v33 offset0:148 offset1:156
	ds_read2_b32 v[52:53], v33 offset0:181 offset1:189
	ds_read2_b32 v[54:55], v33 offset0:214 offset1:222
	ds_read2_b32 v[58:59], v33 offset0:247 offset1:255
	v_lshl_add_u64 v[4:5], v[56:57], 0, v[4:5]
	global_store_dwordx4 v[4:5], v[0:3], off nt
	v_or_b32_e32 v4, s16, v35
	v_mul_u32_u24_e32 v4, 0xb00, v4
	v_lshlrev_b32_e32 v4, 1, v4
	v_mov_b32_e32 v5, v9
	s_waitcnt lgkmcnt(6)
	v_cvt_pk_bf16_f32 v0, v6, v44
	s_waitcnt lgkmcnt(4)
	v_cvt_pk_bf16_f32 v1, v46, v48
	s_waitcnt lgkmcnt(2)
	v_cvt_pk_bf16_f32 v2, v50, v52
	s_waitcnt lgkmcnt(0)
	v_cvt_pk_bf16_f32 v3, v54, v58
	v_lshl_add_u64 v[4:5], v[56:57], 0, v[4:5]
	global_store_dwordx4 v[4:5], v[0:3], off nt
	v_or_b32_e32 v4, s16, v36
	v_mul_u32_u24_e32 v4, 0xb00, v4
	v_lshlrev_b32_e32 v4, 1, v4
	v_mov_b32_e32 v5, v9
	v_cvt_pk_bf16_f32 v0, v7, v45
	v_cvt_pk_bf16_f32 v1, v47, v49
	v_cvt_pk_bf16_f32 v2, v51, v53
	v_cvt_pk_bf16_f32 v3, v55, v59
	v_lshl_add_u64 v[4:5], v[56:57], 0, v[4:5]
	global_store_dwordx4 v[4:5], v[0:3], off nt
	s_waitcnt lgkmcnt(0)
	s_mov_b64 s[16:17], 0

.LBB0_39:
	s_waitcnt vmcnt(16)
	s_waitcnt vmcnt(0)
	ds_write2_b32 v31, v27, v44 offset1:66
	ds_write2_b32 v31, v45, v46 offset0:132 offset1:198
	ds_write2_b32 v37, v47, v48 offset0:8 offset1:74
	ds_write2_b32 v37, v49, v50 offset0:140 offset1:206
	ds_write2_b32 v38, v51, v52 offset0:16 offset1:82
	ds_write2_b32 v38, v53, v54 offset0:148 offset1:214
	ds_write2_b32 v39, v55, v56 offset0:24 offset1:90
	ds_write2_b32 v39, v57, v58 offset0:156 offset1:222
	ds_write2_b32 v40, v59, v60 offset0:32 offset1:98
	ds_write2_b32 v40, v61, v62 offset0:164 offset1:230
	ds_write2_b32 v41, v63, v64 offset0:40 offset1:106
	ds_write2_b32 v41, v65, v66 offset0:172 offset1:238
	ds_write2_b32 v42, v67, v68 offset0:48 offset1:114
	ds_write2_b32 v42, v69, v70 offset0:180 offset1:246
	ds_write2_b32 v43, v71, v72 offset0:56 offset1:122
	ds_write2_b32 v43, v73, v74 offset0:188 offset1:254
	s_waitcnt lgkmcnt(0)
	ds_read2_b32 v[48:49], v33 offset1:8
	ds_read2_b32 v[50:51], v33 offset0:33 offset1:41
	ds_read2_b32 v[54:55], v33 offset0:66 offset1:74
	ds_read2_b32 v[56:57], v33 offset0:99 offset1:107
	ds_read2_b32 v[58:59], v33 offset0:132 offset1:140
	ds_read2_b32 v[60:61], v33 offset0:165 offset1:173
	ds_read2_b32 v[62:63], v33 offset0:198 offset1:206
	ds_read2_b32 v[64:65], v33 offset0:231 offset1:239
	s_and_b64 s[16:17], s[16:17], exec
	s_cselect_b32 s16, 0xb00000, 0
	s_waitcnt lgkmcnt(7)
	v_mov_b32_e32 v44, v48
	s_waitcnt lgkmcnt(6)
	v_mov_b32_e32 v45, v50
	s_waitcnt lgkmcnt(5)
	v_mov_b32_e32 v46, v54
	s_waitcnt lgkmcnt(4)
	v_mov_b32_e32 v47, v56
	s_add_u32 s16, s36, s16
	v_pk_mul_f32 v[44:45], v[4:5], v[44:45]
	v_pk_mul_f32 v[46:47], v[6:7], v[46:47]
	s_addc_u32 s17, s37, 0
	s_lshl_b32 s6, s6, 1
	v_cvt_pk_bf16_f32 v44, v44, v45
	v_cvt_pk_bf16_f32 v45, v46, v47
	s_waitcnt lgkmcnt(3)
	v_mov_b32_e32 v46, v58
	s_waitcnt lgkmcnt(2)
	v_mov_b32_e32 v47, v60
	s_waitcnt lgkmcnt(1)
	v_mov_b32_e32 v66, v62
	s_waitcnt lgkmcnt(0)
	v_mov_b32_e32 v67, v64
	s_add_u32 s16, s16, s6
	v_pk_mul_f32 v[46:47], v[0:1], v[46:47]
	v_pk_mul_f32 v[66:67], v[2:3], v[66:67]
	s_addc_u32 s17, s17, 0
	v_mov_b32_e32 v27, v9
	v_cvt_pk_bf16_f32 v46, v46, v47
	v_cvt_pk_bf16_f32 v47, v66, v67
	v_add_u32_e32 v66, s72, v32
	v_mov_b32_e32 v67, v9
	v_lshl_add_u64 v[52:53], s[16:17], 0, v[26:27]
	v_lshlrev_b64 v[66:67], 11, v[66:67]
	v_lshl_add_u64 v[66:67], v[52:53], 0, v[66:67]
	v_mov_b32_e32 v50, v49
	v_mov_b32_e32 v56, v55
	global_store_dwordx4 v[66:67], v[44:47], off nt
	v_mov_b32_e32 v60, v59
	v_mov_b32_e32 v64, v63
	v_pk_mul_f32 v[44:45], v[4:5], v[50:51]
	v_pk_mul_f32 v[46:47], v[6:7], v[56:57]
	v_cvt_pk_bf16_f32 v44, v44, v45
	v_cvt_pk_bf16_f32 v45, v46, v47
	v_pk_mul_f32 v[46:47], v[0:1], v[60:61]
	v_pk_mul_f32 v[48:49], v[2:3], v[64:65]
	v_cvt_pk_bf16_f32 v46, v46, v47
	v_cvt_pk_bf16_f32 v47, v48, v49
	v_add_u32_e32 v48, s72, v34
	v_mov_b32_e32 v49, v9
	v_lshlrev_b64 v[48:49], 11, v[48:49]
	v_lshl_add_u64 v[48:49], v[52:53], 0, v[48:49]
	ds_read2_b32 v[50:51], v33 offset0:16 offset1:24
	ds_read2_b32 v[54:55], v33 offset0:49 offset1:57
	global_store_dwordx4 v[48:49], v[44:47], off nt
	ds_read2_b32 v[48:49], v33 offset0:82 offset1:90
	ds_read2_b32 v[56:57], v33 offset0:115 offset1:123
	ds_read2_b32 v[58:59], v33 offset0:148 offset1:156
	ds_read2_b32 v[60:61], v33 offset0:181 offset1:189
	ds_read2_b32 v[62:63], v33 offset0:214 offset1:222
	ds_read2_b32 v[64:65], v33 offset0:247 offset1:255
	s_waitcnt lgkmcnt(7)
	v_mov_b32_e32 v44, v50
	s_waitcnt lgkmcnt(6)
	v_mov_b32_e32 v45, v54
	s_waitcnt lgkmcnt(5)
	v_mov_b32_e32 v46, v48
	s_waitcnt lgkmcnt(4)
	v_mov_b32_e32 v47, v56
	v_pk_mul_f32 v[44:45], v[4:5], v[44:45]
	v_pk_mul_f32 v[46:47], v[6:7], v[46:47]
	v_cvt_pk_bf16_f32 v44, v44, v45
	v_cvt_pk_bf16_f32 v45, v46, v47
	s_waitcnt lgkmcnt(3)
	v_mov_b32_e32 v46, v58
	s_waitcnt lgkmcnt(2)
	v_mov_b32_e32 v47, v60
	v_mov_b32_e32 v54, v51
	v_mov_b32_e32 v56, v49
	v_mov_b32_e32 v60, v59
	v_pk_mul_f32 v[46:47], v[0:1], v[46:47]
	s_waitcnt lgkmcnt(1)
	v_mov_b32_e32 v66, v62
	s_waitcnt lgkmcnt(0)
	v_mov_b32_e32 v67, v64
	v_pk_mul_f32 v[4:5], v[4:5], v[54:55]
	v_pk_mul_f32 v[6:7], v[6:7], v[56:57]
	v_pk_mul_f32 v[0:1], v[0:1], v[60:61]
	v_mov_b32_e32 v64, v63
	v_pk_mul_f32 v[66:67], v[2:3], v[66:67]
	v_cvt_pk_bf16_f32 v4, v4, v5
	v_cvt_pk_bf16_f32 v5, v6, v7
	v_cvt_pk_bf16_f32 v6, v0, v1
	v_pk_mul_f32 v[0:1], v[2:3], v[64:65]
	v_cvt_pk_bf16_f32 v46, v46, v47
	v_cvt_pk_bf16_f32 v47, v66, v67
	v_add_u32_e32 v66, s72, v35
	v_mov_b32_e32 v67, v9
	v_cvt_pk_bf16_f32 v7, v0, v1
	v_add_u32_e32 v0, s72, v36
	v_mov_b32_e32 v1, v9
	v_lshlrev_b64 v[66:67], 11, v[66:67]
	v_lshlrev_b64 v[0:1], 11, v[0:1]
	v_lshl_add_u64 v[66:67], v[52:53], 0, v[66:67]
	v_lshl_add_u64 v[0:1], v[52:53], 0, v[0:1]
	global_store_dwordx4 v[66:67], v[44:47], off nt
	global_store_dwordx4 v[0:1], v[4:7], off nt
	s_waitcnt lgkmcnt(0)
	s_mov_b32 s92, s91
	v_readlane_b32 s72, v254, 10

.LBB0_41:
	s_andn2_b64 vcc, exec, s[16:17]
	s_cbranch_vccnz .LBB0_43
	s_and_b32 s6, s40, 0x3fc0
	s_add_i32 s16, s6, 0xffffcc00
	v_or_b32_e32 v0, s16, v30
	v_mov_b32_e32 v1, v9
	s_and_b32 s26, s38, 0x3e0
	v_lshlrev_b64 v[0:1], 12, v[0:1]
	v_lshl_add_u64 v[0:1], s[18:19], 0, v[0:1]
	s_lshl_b32 s6, s26, 2
	v_lshl_add_u64 v[0:1], v[0:1], 0, s[6:7]
	v_lshl_add_u64 v[0:1], v[0:1], 0, v[8:9]
	v_add_co_u32_e32 v2, vcc, 0x2000, v0
	s_mov_b32 s17, s7
	s_nop 0
	v_addc_co_u32_e32 v3, vcc, 0, v1, vcc
	v_add_co_u32_e32 v4, vcc, 0x4000, v0
	s_nop 1
	v_addc_co_u32_e32 v5, vcc, 0, v1, vcc
	v_add_co_u32_e32 v6, vcc, 0x6000, v0
	s_nop 1
	v_addc_co_u32_e32 v7, vcc, 0, v1, vcc
	v_add_co_u32_e32 v44, vcc, 0x8000, v0
	s_nop 1
	v_addc_co_u32_e32 v45, vcc, 0, v1, vcc
	v_add_co_u32_e32 v46, vcc, 0xa000, v0
	s_nop 1
	v_addc_co_u32_e32 v47, vcc, 0, v1, vcc
	v_add_co_u32_e32 v48, vcc, 0xc000, v0
	s_nop 1
	v_addc_co_u32_e32 v49, vcc, 0, v1, vcc
	v_add_co_u32_e32 v50, vcc, 0xe000, v0
	s_nop 1
	v_addc_co_u32_e32 v51, vcc, 0, v1, vcc
	global_load_dword v27, v[0:1], off nt
	global_load_dword v54, v[2:3], off nt
	global_load_dword v55, v[4:5], off nt
	global_load_dword v56, v[6:7], off nt
	global_load_dword v57, v[44:45], off nt
	global_load_dword v58, v[46:47], off nt
	global_load_dword v59, v[48:49], off nt
	global_load_dword v60, v[50:51], off nt
	v_add_co_u32_e32 v2, vcc, 0x10000, v0
	s_nop 1
	v_addc_co_u32_e32 v3, vcc, 0, v1, vcc
	v_add_co_u32_e32 v4, vcc, 0x12000, v0
	s_nop 1
	v_addc_co_u32_e32 v5, vcc, 0, v1, vcc
	v_add_co_u32_e32 v6, vcc, 0x14000, v0
	s_nop 1
	v_addc_co_u32_e32 v7, vcc, 0, v1, vcc
	v_add_co_u32_e32 v44, vcc, 0x16000, v0
	s_nop 1
	v_addc_co_u32_e32 v45, vcc, 0, v1, vcc
	v_add_co_u32_e32 v46, vcc, 0x18000, v0
	s_nop 1
	v_addc_co_u32_e32 v47, vcc, 0, v1, vcc
	v_add_co_u32_e32 v48, vcc, 0x1a000, v0
	s_nop 1
	v_addc_co_u32_e32 v49, vcc, 0, v1, vcc
	v_add_co_u32_e32 v50, vcc, 0x1c000, v0
	s_nop 1
	v_addc_co_u32_e32 v51, vcc, 0, v1, vcc
	v_add_co_u32_e32 v52, vcc, 0x1e000, v0
	s_nop 1
	v_addc_co_u32_e32 v53, vcc, 0, v1, vcc
	global_load_dword v61, v[2:3], off nt
	global_load_dword v62, v[4:5], off nt
	global_load_dword v63, v[6:7], off nt
	global_load_dword v64, v[44:45], off nt
	global_load_dword v65, v[46:47], off nt
	global_load_dword v66, v[48:49], off nt
	global_load_dword v67, v[50:51], off nt
	global_load_dword v68, v[52:53], off nt
	v_add_co_u32_e32 v2, vcc, 0x20000, v0
	s_nop 1
	v_addc_co_u32_e32 v3, vcc, 0, v1, vcc
	v_add_co_u32_e32 v4, vcc, 0x22000, v0
	s_nop 1
	v_addc_co_u32_e32 v5, vcc, 0, v1, vcc
	v_add_co_u32_e32 v6, vcc, 0x24000, v0
	s_nop 1
	v_addc_co_u32_e32 v7, vcc, 0, v1, vcc
	v_add_co_u32_e32 v44, vcc, 0x26000, v0
	s_nop 1
	v_addc_co_u32_e32 v45, vcc, 0, v1, vcc
	v_add_co_u32_e32 v46, vcc, 0x28000, v0
	s_nop 1
	v_addc_co_u32_e32 v47, vcc, 0, v1, vcc
	v_add_co_u32_e32 v48, vcc, 0x2a000, v0
	s_nop 1
	v_addc_co_u32_e32 v49, vcc, 0, v1, vcc
	v_add_co_u32_e32 v50, vcc, 0x2c000, v0
	s_nop 1
	v_addc_co_u32_e32 v51, vcc, 0, v1, vcc
	v_add_co_u32_e32 v52, vcc, 0x2e000, v0
	s_nop 1
	v_addc_co_u32_e32 v53, vcc, 0, v1, vcc
	global_load_dword v69, v[2:3], off nt
	global_load_dword v70, v[4:5], off nt
	global_load_dword v71, v[6:7], off nt
	global_load_dword v72, v[44:45], off nt
	global_load_dword v73, v[46:47], off nt
	global_load_dword v74, v[48:49], off nt
	global_load_dword v75, v[50:51], off nt
	s_nop 0
	global_load_dword v52, v[52:53], off nt
	v_add_co_u32_e32 v2, vcc, 0x30000, v0
	s_nop 1
	v_addc_co_u32_e32 v3, vcc, 0, v1, vcc
	v_add_co_u32_e32 v4, vcc, 0x32000, v0
	s_nop 1
	v_addc_co_u32_e32 v5, vcc, 0, v1, vcc
	v_add_co_u32_e32 v6, vcc, 0x34000, v0
	s_nop 1
	v_addc_co_u32_e32 v7, vcc, 0, v1, vcc
	v_add_co_u32_e32 v44, vcc, 0x36000, v0
	s_nop 1
	v_addc_co_u32_e32 v45, vcc, 0, v1, vcc
	v_add_co_u32_e32 v46, vcc, 0x38000, v0
	s_nop 1
	v_addc_co_u32_e32 v47, vcc, 0, v1, vcc
	v_add_co_u32_e32 v48, vcc, 0x3a000, v0
	s_nop 1
	v_addc_co_u32_e32 v49, vcc, 0, v1, vcc
	v_add_co_u32_e32 v50, vcc, 0x3c000, v0
	s_nop 1
	v_addc_co_u32_e32 v51, vcc, 0, v1, vcc
	v_add_co_u32_e32 v0, vcc, 0x3e000, v0
	s_nop 1
	v_addc_co_u32_e32 v1, vcc, 0, v1, vcc
	global_load_dword v2, v[2:3], off nt
	s_nop 0
	global_load_dword v3, v[4:5], off nt
	s_nop 0
	global_load_dword v4, v[6:7], off nt
	global_load_dword v5, v[44:45], off nt
	s_nop 0
	global_load_dword v6, v[46:47], off nt
	global_load_dword v7, v[48:49], off nt
	global_load_dword v44, v[50:51], off nt
	s_nop 0
	global_load_dword v0, v[0:1], off nt
	s_waitcnt vmcnt(16)
	s_waitcnt vmcnt(0)
	ds_write2_b32 v31, v27, v54 offset1:66
	ds_write2_b32 v31, v55, v56 offset0:132 offset1:198
	ds_write2_b32 v37, v57, v58 offset0:8 offset1:74
	ds_write2_b32 v37, v59, v60 offset0:140 offset1:206
	ds_write2_b32 v38, v61, v62 offset0:16 offset1:82
	ds_write2_b32 v38, v63, v64 offset0:148 offset1:214
	ds_write2_b32 v39, v65, v66 offset0:24 offset1:90
	ds_write2_b32 v39, v67, v68 offset0:156 offset1:222
	ds_write2_b32 v40, v69, v70 offset0:32 offset1:98
	ds_write2_b32 v40, v71, v72 offset0:164 offset1:230
	ds_write2_b32 v41, v73, v74 offset0:40 offset1:106
	ds_write2_b32 v41, v75, v52 offset0:172 offset1:238
	ds_write2_b32 v42, v2, v3 offset0:48 offset1:114
	ds_write2_b32 v42, v4, v5 offset0:180 offset1:246
	ds_write2_b32 v43, v6, v7 offset0:56 offset1:122
	ds_write2_b32 v43, v44, v0 offset0:188 offset1:254
	s_waitcnt lgkmcnt(0)
	ds_read2_b32 v[4:5], v33 offset0:33 offset1:41
	ds_read2_b32 v[6:7], v33 offset1:8
	ds_read2_b32 v[44:45], v33 offset0:66 offset1:74
	ds_read2_b32 v[46:47], v33 offset0:99 offset1:107
	ds_read2_b32 v[48:49], v33 offset0:132 offset1:140
	ds_read2_b32 v[50:51], v33 offset0:165 offset1:173
	ds_read2_b32 v[52:53], v33 offset0:198 offset1:206
	ds_read2_b32 v[54:55], v33 offset0:231 offset1:239
	s_waitcnt lgkmcnt(6)
	v_cvt_pk_bf16_f32 v0, v6, v4
	v_or_b32_e32 v4, s26, v32
	v_lshl_add_u64 v[56:57], s[16:17], 1, v[12:13]
	v_lshlrev_b32_e32 v58, 11, v4
	v_mov_b32_e32 v59, v9
	s_waitcnt lgkmcnt(4)
	v_cvt_pk_bf16_f32 v1, v44, v46
	s_waitcnt lgkmcnt(2)
	v_cvt_pk_bf16_f32 v2, v48, v50
	s_waitcnt lgkmcnt(0)
	v_cvt_pk_bf16_f32 v3, v52, v54
	v_lshl_add_u64 v[58:59], v[56:57], 0, v[58:59]
	global_store_dwordx4 v[58:59], v[0:3], off nt
	v_or_b32_e32 v4, s26, v34
	v_lshlrev_b32_e32 v4, 11, v4
	v_cvt_pk_bf16_f32 v0, v7, v5
	v_cvt_pk_bf16_f32 v1, v45, v47
	v_cvt_pk_bf16_f32 v2, v49, v51
	v_cvt_pk_bf16_f32 v3, v53, v55
	ds_read2_b32 v[6:7], v33 offset0:49 offset1:57
	ds_read2_b32 v[44:45], v33 offset0:16 offset1:24
	ds_read2_b32 v[46:47], v33 offset0:82 offset1:90
	ds_read2_b32 v[48:49], v33 offset0:115 offset1:123
	ds_read2_b32 v[50:51], v33 offset0:148 offset1:156
	ds_read2_b32 v[52:53], v33 offset0:181 offset1:189
	ds_read2_b32 v[54:55], v33 offset0:214 offset1:222
	ds_read2_b32 v[58:59], v33 offset0:247 offset1:255
	v_mov_b32_e32 v5, v9
	v_lshl_add_u64 v[4:5], v[56:57], 0, v[4:5]
	global_store_dwordx4 v[4:5], v[0:3], off nt
	v_or_b32_e32 v4, s26, v35
	v_lshlrev_b32_e32 v4, 11, v4
	v_mov_b32_e32 v5, v9
	s_waitcnt lgkmcnt(6)
	v_cvt_pk_bf16_f32 v0, v44, v6
	s_waitcnt lgkmcnt(4)
	v_cvt_pk_bf16_f32 v1, v46, v48
	s_waitcnt lgkmcnt(2)
	v_cvt_pk_bf16_f32 v2, v50, v52
	s_waitcnt lgkmcnt(0)
	v_cvt_pk_bf16_f32 v3, v54, v58
	v_lshl_add_u64 v[4:5], v[56:57], 0, v[4:5]
	global_store_dwordx4 v[4:5], v[0:3], off nt
	v_or_b32_e32 v4, s26, v36
	v_lshlrev_b32_e32 v4, 11, v4
	v_mov_b32_e32 v5, v9
	v_cvt_pk_bf16_f32 v0, v45, v7
	v_cvt_pk_bf16_f32 v1, v47, v49
	v_cvt_pk_bf16_f32 v2, v51, v53
	v_cvt_pk_bf16_f32 v3, v55, v59
	v_lshl_add_u64 v[4:5], v[56:57], 0, v[4:5]
	global_store_dwordx4 v[4:5], v[0:3], off nt
	s_waitcnt lgkmcnt(0)

.LBB0_48:
	s_waitcnt vmcnt(16)
	s_waitcnt vmcnt(0)
	ds_write2_b32 v31, v27, v44 offset1:66
	ds_write2_b32 v31, v45, v46 offset0:132 offset1:198
	ds_write2_b32 v37, v47, v48 offset0:8 offset1:74
	ds_write2_b32 v37, v49, v50 offset0:140 offset1:206
	ds_write2_b32 v38, v51, v52 offset0:16 offset1:82
	ds_write2_b32 v38, v53, v54 offset0:148 offset1:214
	ds_write2_b32 v39, v55, v56 offset0:24 offset1:90
	ds_write2_b32 v39, v57, v58 offset0:156 offset1:222
	ds_write2_b32 v40, v59, v60 offset0:32 offset1:98
	ds_write2_b32 v40, v61, v62 offset0:164 offset1:230
	ds_write2_b32 v41, v63, v64 offset0:40 offset1:106
	ds_write2_b32 v41, v65, v66 offset0:172 offset1:238
	ds_write2_b32 v42, v67, v68 offset0:48 offset1:114
	ds_write2_b32 v42, v69, v70 offset0:180 offset1:246
	ds_write2_b32 v43, v71, v72 offset0:56 offset1:122
	ds_write2_b32 v43, v73, v74 offset0:188 offset1:254
	s_waitcnt lgkmcnt(0)
	ds_read2_b32 v[48:49], v33 offset1:8
	ds_read2_b32 v[50:51], v33 offset0:33 offset1:41
	ds_read2_b32 v[54:55], v33 offset0:66 offset1:74
	ds_read2_b32 v[56:57], v33 offset0:99 offset1:107
	ds_read2_b32 v[58:59], v33 offset0:132 offset1:140
	ds_read2_b32 v[60:61], v33 offset0:165 offset1:173
	ds_read2_b32 v[62:63], v33 offset0:198 offset1:206
	ds_read2_b32 v[64:65], v33 offset0:231 offset1:239
	s_waitcnt lgkmcnt(7)
	v_mov_b32_e32 v44, v48
	s_waitcnt lgkmcnt(6)
	v_mov_b32_e32 v45, v50
	s_waitcnt lgkmcnt(5)
	v_mov_b32_e32 v46, v54
	s_waitcnt lgkmcnt(4)
	v_mov_b32_e32 v47, v56
	v_pk_mul_f32 v[44:45], v[4:5], v[44:45]
	v_pk_mul_f32 v[46:47], v[6:7], v[46:47]
	v_cvt_pk_bf16_f32 v44, v44, v45
	v_cvt_pk_bf16_f32 v45, v46, v47
	s_waitcnt lgkmcnt(3)
	v_mov_b32_e32 v46, v58
	s_waitcnt lgkmcnt(2)
	v_mov_b32_e32 v47, v60
	s_waitcnt lgkmcnt(1)
	v_mov_b32_e32 v66, v62
	s_waitcnt lgkmcnt(0)
	v_mov_b32_e32 v67, v64
	v_pk_mul_f32 v[46:47], v[0:1], v[46:47]
	v_pk_mul_f32 v[66:67], v[2:3], v[66:67]
	v_or_b32_e32 v27, s16, v32
	v_lshl_add_u64 v[52:53], s[6:7], 1, v[16:17]
	v_cvt_pk_bf16_f32 v46, v46, v47
	v_cvt_pk_bf16_f32 v47, v66, v67
	v_lshlrev_b32_e32 v66, 11, v27
	v_mov_b32_e32 v67, v9
	v_lshl_add_u64 v[66:67], v[52:53], 0, v[66:67]
	v_mov_b32_e32 v50, v49
	v_mov_b32_e32 v56, v55
	global_store_dwordx4 v[66:67], v[44:47], off nt
	v_mov_b32_e32 v60, v59
	v_mov_b32_e32 v64, v63
	v_pk_mul_f32 v[44:45], v[4:5], v[50:51]
	v_pk_mul_f32 v[46:47], v[6:7], v[56:57]
	v_cvt_pk_bf16_f32 v44, v44, v45
	v_cvt_pk_bf16_f32 v45, v46, v47
	v_pk_mul_f32 v[46:47], v[0:1], v[60:61]
	v_pk_mul_f32 v[48:49], v[2:3], v[64:65]
	v_or_b32_e32 v27, s16, v34
	v_cvt_pk_bf16_f32 v46, v46, v47
	v_cvt_pk_bf16_f32 v47, v48, v49
	v_lshlrev_b32_e32 v48, 11, v27
	v_mov_b32_e32 v49, v9
	v_lshl_add_u64 v[48:49], v[52:53], 0, v[48:49]
	ds_read2_b32 v[50:51], v33 offset0:16 offset1:24
	ds_read2_b32 v[54:55], v33 offset0:49 offset1:57
	global_store_dwordx4 v[48:49], v[44:47], off nt
	ds_read2_b32 v[48:49], v33 offset0:82 offset1:90
	ds_read2_b32 v[56:57], v33 offset0:115 offset1:123
	ds_read2_b32 v[58:59], v33 offset0:148 offset1:156
	ds_read2_b32 v[60:61], v33 offset0:181 offset1:189
	ds_read2_b32 v[62:63], v33 offset0:214 offset1:222
	ds_read2_b32 v[64:65], v33 offset0:247 offset1:255
	s_waitcnt lgkmcnt(7)
	v_mov_b32_e32 v44, v50
	s_waitcnt lgkmcnt(6)
	v_mov_b32_e32 v45, v54
	s_waitcnt lgkmcnt(5)
	v_mov_b32_e32 v46, v48
	s_waitcnt lgkmcnt(4)
	v_mov_b32_e32 v47, v56
	v_pk_mul_f32 v[44:45], v[4:5], v[44:45]
	v_pk_mul_f32 v[46:47], v[6:7], v[46:47]
	v_cvt_pk_bf16_f32 v44, v44, v45
	v_cvt_pk_bf16_f32 v45, v46, v47
	s_waitcnt lgkmcnt(3)
	v_mov_b32_e32 v46, v58
	s_waitcnt lgkmcnt(2)
	v_mov_b32_e32 v47, v60
	v_mov_b32_e32 v54, v51
	v_mov_b32_e32 v56, v49
	v_mov_b32_e32 v60, v59
	v_pk_mul_f32 v[46:47], v[0:1], v[46:47]
	s_waitcnt lgkmcnt(0)
	v_mov_b32_e32 v67, v64
	v_pk_mul_f32 v[4:5], v[4:5], v[54:55]
	v_pk_mul_f32 v[6:7], v[6:7], v[56:57]
	v_pk_mul_f32 v[0:1], v[0:1], v[60:61]
	v_mov_b32_e32 v64, v63
	v_mov_b32_e32 v66, v62
	v_cvt_pk_bf16_f32 v4, v4, v5
	v_cvt_pk_bf16_f32 v5, v6, v7
	v_cvt_pk_bf16_f32 v6, v0, v1
	v_pk_mul_f32 v[0:1], v[2:3], v[64:65]
	v_pk_mul_f32 v[66:67], v[2:3], v[66:67]
	v_or_b32_e32 v27, s16, v35
	v_cvt_pk_bf16_f32 v7, v0, v1
	v_or_b32_e32 v0, s16, v36
	v_cvt_pk_bf16_f32 v46, v46, v47
	v_cvt_pk_bf16_f32 v47, v66, v67
	v_lshlrev_b32_e32 v66, 11, v27
	v_mov_b32_e32 v67, v9
	v_lshlrev_b32_e32 v0, 11, v0
	v_mov_b32_e32 v1, v9
	v_lshl_add_u64 v[66:67], v[52:53], 0, v[66:67]
	v_lshl_add_u64 v[0:1], v[52:53], 0, v[0:1]
	global_store_dwordx4 v[66:67], v[44:47], off nt
	global_store_dwordx4 v[0:1], v[4:7], off nt
	s_waitcnt lgkmcnt(0)

.LBB0_54:
	s_waitcnt vmcnt(16)
	s_waitcnt vmcnt(0)
	ds_write2_b32 v31, v27, v44 offset1:66
	ds_write2_b32 v31, v45, v46 offset0:132 offset1:198
	ds_write2_b32 v37, v47, v48 offset0:8 offset1:74
	ds_write2_b32 v37, v49, v50 offset0:140 offset1:206
	ds_write2_b32 v38, v51, v52 offset0:16 offset1:82
	ds_write2_b32 v38, v53, v54 offset0:148 offset1:214
	ds_write2_b32 v39, v55, v56 offset0:24 offset1:90
	ds_write2_b32 v39, v57, v58 offset0:156 offset1:222
	ds_write2_b32 v40, v59, v60 offset0:32 offset1:98
	ds_write2_b32 v40, v61, v62 offset0:164 offset1:230
	ds_write2_b32 v41, v63, v64 offset0:40 offset1:106
	ds_write2_b32 v41, v65, v66 offset0:172 offset1:238
	ds_write2_b32 v42, v67, v68 offset0:48 offset1:114
	ds_write2_b32 v42, v69, v70 offset0:180 offset1:246
	ds_write2_b32 v43, v71, v72 offset0:56 offset1:122
	ds_write2_b32 v43, v73, v74 offset0:188 offset1:254
	s_waitcnt lgkmcnt(0)
	ds_read2_b32 v[48:49], v33 offset1:8
	ds_read2_b32 v[50:51], v33 offset0:33 offset1:41
	ds_read2_b32 v[54:55], v33 offset0:66 offset1:74
	ds_read2_b32 v[56:57], v33 offset0:99 offset1:107
	ds_read2_b32 v[58:59], v33 offset0:132 offset1:140
	ds_read2_b32 v[60:61], v33 offset0:165 offset1:173
	ds_read2_b32 v[62:63], v33 offset0:198 offset1:206
	ds_read2_b32 v[64:65], v33 offset0:231 offset1:239
	s_waitcnt lgkmcnt(7)
	v_mov_b32_e32 v44, v48
	s_waitcnt lgkmcnt(6)
	v_mov_b32_e32 v45, v50
	s_waitcnt lgkmcnt(5)
	v_mov_b32_e32 v46, v54
	s_waitcnt lgkmcnt(4)
	v_mov_b32_e32 v47, v56
	v_pk_mul_f32 v[44:45], v[4:5], v[44:45]
	v_pk_mul_f32 v[46:47], v[6:7], v[46:47]
	v_cvt_pk_bf16_f32 v44, v44, v45
	v_cvt_pk_bf16_f32 v45, v46, v47
	s_waitcnt lgkmcnt(3)
	v_mov_b32_e32 v46, v58
	s_waitcnt lgkmcnt(2)
	v_mov_b32_e32 v47, v60
	s_waitcnt lgkmcnt(1)
	v_mov_b32_e32 v66, v62
	s_waitcnt lgkmcnt(0)
	v_mov_b32_e32 v67, v64
	v_pk_mul_f32 v[46:47], v[0:1], v[46:47]
	v_pk_mul_f32 v[66:67], v[2:3], v[66:67]
	v_or_b32_e32 v27, s16, v32
	v_lshl_add_u64 v[52:53], s[6:7], 1, v[18:19]
	v_cvt_pk_bf16_f32 v46, v46, v47
	v_cvt_pk_bf16_f32 v47, v66, v67
	v_lshlrev_b32_e32 v66, 11, v27
	v_mov_b32_e32 v67, v9
	v_lshl_add_u64 v[66:67], v[52:53], 0, v[66:67]
	v_mov_b32_e32 v50, v49
	v_mov_b32_e32 v56, v55
	global_store_dwordx4 v[66:67], v[44:47], off nt
	v_mov_b32_e32 v60, v59
	v_mov_b32_e32 v64, v63
	v_pk_mul_f32 v[44:45], v[4:5], v[50:51]
	v_pk_mul_f32 v[46:47], v[6:7], v[56:57]
	v_cvt_pk_bf16_f32 v44, v44, v45
	v_cvt_pk_bf16_f32 v45, v46, v47
	v_pk_mul_f32 v[46:47], v[0:1], v[60:61]
	v_pk_mul_f32 v[48:49], v[2:3], v[64:65]
	v_or_b32_e32 v27, s16, v34
	v_cvt_pk_bf16_f32 v46, v46, v47
	v_cvt_pk_bf16_f32 v47, v48, v49
	v_lshlrev_b32_e32 v48, 11, v27
	v_mov_b32_e32 v49, v9
	v_lshl_add_u64 v[48:49], v[52:53], 0, v[48:49]
	ds_read2_b32 v[50:51], v33 offset0:16 offset1:24
	ds_read2_b32 v[54:55], v33 offset0:49 offset1:57
	global_store_dwordx4 v[48:49], v[44:47], off nt
	ds_read2_b32 v[48:49], v33 offset0:82 offset1:90
	ds_read2_b32 v[56:57], v33 offset0:115 offset1:123
	ds_read2_b32 v[58:59], v33 offset0:148 offset1:156
	ds_read2_b32 v[60:61], v33 offset0:181 offset1:189
	ds_read2_b32 v[62:63], v33 offset0:214 offset1:222
	ds_read2_b32 v[64:65], v33 offset0:247 offset1:255
	s_waitcnt lgkmcnt(7)
	v_mov_b32_e32 v44, v50
	s_waitcnt lgkmcnt(6)
	v_mov_b32_e32 v45, v54
	s_waitcnt lgkmcnt(5)
	v_mov_b32_e32 v46, v48
	s_waitcnt lgkmcnt(4)
	v_mov_b32_e32 v47, v56
	v_pk_mul_f32 v[44:45], v[4:5], v[44:45]
	v_pk_mul_f32 v[46:47], v[6:7], v[46:47]
	v_cvt_pk_bf16_f32 v44, v44, v45
	v_cvt_pk_bf16_f32 v45, v46, v47
	s_waitcnt lgkmcnt(3)
	v_mov_b32_e32 v46, v58
	s_waitcnt lgkmcnt(2)
	v_mov_b32_e32 v47, v60
	v_mov_b32_e32 v54, v51
	v_mov_b32_e32 v56, v49
	v_mov_b32_e32 v60, v59
	v_pk_mul_f32 v[46:47], v[0:1], v[46:47]
	s_waitcnt lgkmcnt(0)
	v_mov_b32_e32 v67, v64
	v_pk_mul_f32 v[4:5], v[4:5], v[54:55]
	v_pk_mul_f32 v[6:7], v[6:7], v[56:57]
	v_pk_mul_f32 v[0:1], v[0:1], v[60:61]
	v_mov_b32_e32 v64, v63
	v_mov_b32_e32 v66, v62
	v_cvt_pk_bf16_f32 v4, v4, v5
	v_cvt_pk_bf16_f32 v5, v6, v7
	v_cvt_pk_bf16_f32 v6, v0, v1
	v_pk_mul_f32 v[0:1], v[2:3], v[64:65]
	v_pk_mul_f32 v[66:67], v[2:3], v[66:67]
	v_or_b32_e32 v27, s16, v35
	v_cvt_pk_bf16_f32 v7, v0, v1
	v_or_b32_e32 v0, s16, v36
	v_cvt_pk_bf16_f32 v46, v46, v47
	v_cvt_pk_bf16_f32 v47, v66, v67
	v_lshlrev_b32_e32 v66, 11, v27
	v_mov_b32_e32 v67, v9
	v_lshlrev_b32_e32 v0, 11, v0
	v_mov_b32_e32 v1, v9
	v_lshl_add_u64 v[66:67], v[52:53], 0, v[66:67]
	v_lshl_add_u64 v[0:1], v[52:53], 0, v[0:1]
	global_store_dwordx4 v[66:67], v[44:47], off nt
	global_store_dwordx4 v[0:1], v[4:7], off nt
	s_waitcnt lgkmcnt(0)

.LBB0_56:
	s_andn2_b64 vcc, exec, s[16:17]
	s_cbranch_vccnz .LBB0_58
	s_and_b32 s6, s40, 0x3fc0
	s_add_i32 s16, s6, 0xffffdc00
	v_or_b32_e32 v0, s16, v30
	v_mov_b32_e32 v1, v9
	s_and_b32 s26, s38, 0x3e0
	v_lshlrev_b64 v[0:1], 12, v[0:1]
	v_lshl_add_u64 v[0:1], s[10:11], 0, v[0:1]
	s_lshl_b32 s6, s26, 2
	v_lshl_add_u64 v[0:1], v[0:1], 0, s[6:7]
	v_lshl_add_u64 v[0:1], v[0:1], 0, v[8:9]
	v_add_co_u32_e32 v2, vcc, 0x2000, v0
	s_mov_b32 s17, s7
	s_nop 0
	v_addc_co_u32_e32 v3, vcc, 0, v1, vcc
	v_add_co_u32_e32 v4, vcc, 0x4000, v0
	s_nop 1
	v_addc_co_u32_e32 v5, vcc, 0, v1, vcc
	v_add_co_u32_e32 v6, vcc, 0x6000, v0
	s_nop 1
	v_addc_co_u32_e32 v7, vcc, 0, v1, vcc
	v_add_co_u32_e32 v44, vcc, 0x8000, v0
	s_nop 1
	v_addc_co_u32_e32 v45, vcc, 0, v1, vcc
	v_add_co_u32_e32 v46, vcc, 0xa000, v0
	s_nop 1
	v_addc_co_u32_e32 v47, vcc, 0, v1, vcc
	v_add_co_u32_e32 v48, vcc, 0xc000, v0
	s_nop 1
	v_addc_co_u32_e32 v49, vcc, 0, v1, vcc
	v_add_co_u32_e32 v50, vcc, 0xe000, v0
	s_nop 1
	v_addc_co_u32_e32 v51, vcc, 0, v1, vcc
	global_load_dword v27, v[0:1], off nt
	global_load_dword v54, v[2:3], off nt
	global_load_dword v55, v[4:5], off nt
	global_load_dword v56, v[6:7], off nt
	global_load_dword v57, v[44:45], off nt
	global_load_dword v58, v[46:47], off nt
	global_load_dword v59, v[48:49], off nt
	global_load_dword v60, v[50:51], off nt
	v_add_co_u32_e32 v2, vcc, 0x10000, v0
	s_nop 1
	v_addc_co_u32_e32 v3, vcc, 0, v1, vcc
	v_add_co_u32_e32 v4, vcc, 0x12000, v0
	s_nop 1
	v_addc_co_u32_e32 v5, vcc, 0, v1, vcc
	v_add_co_u32_e32 v6, vcc, 0x14000, v0
	s_nop 1
	v_addc_co_u32_e32 v7, vcc, 0, v1, vcc
	v_add_co_u32_e32 v44, vcc, 0x16000, v0
	s_nop 1
	v_addc_co_u32_e32 v45, vcc, 0, v1, vcc
	v_add_co_u32_e32 v46, vcc, 0x18000, v0
	s_nop 1
	v_addc_co_u32_e32 v47, vcc, 0, v1, vcc
	v_add_co_u32_e32 v48, vcc, 0x1a000, v0
	s_nop 1
	v_addc_co_u32_e32 v49, vcc, 0, v1, vcc
	v_add_co_u32_e32 v50, vcc, 0x1c000, v0
	s_nop 1
	v_addc_co_u32_e32 v51, vcc, 0, v1, vcc
	v_add_co_u32_e32 v52, vcc, 0x1e000, v0
	s_nop 1
	v_addc_co_u32_e32 v53, vcc, 0, v1, vcc
	global_load_dword v61, v[2:3], off nt
	global_load_dword v62, v[4:5], off nt
	global_load_dword v63, v[6:7], off nt
	global_load_dword v64, v[44:45], off nt
	global_load_dword v65, v[46:47], off nt
	global_load_dword v66, v[48:49], off nt
	global_load_dword v67, v[50:51], off nt
	global_load_dword v68, v[52:53], off nt
	v_add_co_u32_e32 v2, vcc, 0x20000, v0
	s_nop 1
	v_addc_co_u32_e32 v3, vcc, 0, v1, vcc
	v_add_co_u32_e32 v4, vcc, 0x22000, v0
	s_nop 1
	v_addc_co_u32_e32 v5, vcc, 0, v1, vcc
	v_add_co_u32_e32 v6, vcc, 0x24000, v0
	s_nop 1
	v_addc_co_u32_e32 v7, vcc, 0, v1, vcc
	v_add_co_u32_e32 v44, vcc, 0x26000, v0
	s_nop 1
	v_addc_co_u32_e32 v45, vcc, 0, v1, vcc
	v_add_co_u32_e32 v46, vcc, 0x28000, v0
	s_nop 1
	v_addc_co_u32_e32 v47, vcc, 0, v1, vcc
	v_add_co_u32_e32 v48, vcc, 0x2a000, v0
	s_nop 1
	v_addc_co_u32_e32 v49, vcc, 0, v1, vcc
	v_add_co_u32_e32 v50, vcc, 0x2c000, v0
	s_nop 1
	v_addc_co_u32_e32 v51, vcc, 0, v1, vcc
	v_add_co_u32_e32 v52, vcc, 0x2e000, v0
	s_nop 1
	v_addc_co_u32_e32 v53, vcc, 0, v1, vcc
	global_load_dword v69, v[2:3], off nt
	global_load_dword v70, v[4:5], off nt
	global_load_dword v71, v[6:7], off nt
	global_load_dword v72, v[44:45], off nt
	global_load_dword v73, v[46:47], off nt
	global_load_dword v74, v[48:49], off nt
	global_load_dword v75, v[50:51], off nt
	s_nop 0
	global_load_dword v52, v[52:53], off nt
	v_add_co_u32_e32 v2, vcc, 0x30000, v0
	s_nop 1
	v_addc_co_u32_e32 v3, vcc, 0, v1, vcc
	v_add_co_u32_e32 v4, vcc, 0x32000, v0
	s_nop 1
	v_addc_co_u32_e32 v5, vcc, 0, v1, vcc
	v_add_co_u32_e32 v6, vcc, 0x34000, v0
	s_nop 1
	v_addc_co_u32_e32 v7, vcc, 0, v1, vcc
	v_add_co_u32_e32 v44, vcc, 0x36000, v0
	s_nop 1
	v_addc_co_u32_e32 v45, vcc, 0, v1, vcc
	v_add_co_u32_e32 v46, vcc, 0x38000, v0
	s_nop 1
	v_addc_co_u32_e32 v47, vcc, 0, v1, vcc
	v_add_co_u32_e32 v48, vcc, 0x3a000, v0
	s_nop 1
	v_addc_co_u32_e32 v49, vcc, 0, v1, vcc
	v_add_co_u32_e32 v50, vcc, 0x3c000, v0
	s_nop 1
	v_addc_co_u32_e32 v51, vcc, 0, v1, vcc
	v_add_co_u32_e32 v0, vcc, 0x3e000, v0
	s_nop 1
	v_addc_co_u32_e32 v1, vcc, 0, v1, vcc
	global_load_dword v2, v[2:3], off nt
	s_nop 0
	global_load_dword v3, v[4:5], off nt
	s_nop 0
	global_load_dword v4, v[6:7], off nt
	global_load_dword v5, v[44:45], off nt
	s_nop 0
	global_load_dword v6, v[46:47], off nt
	global_load_dword v7, v[48:49], off nt
	global_load_dword v44, v[50:51], off nt
	s_nop 0
	global_load_dword v0, v[0:1], off nt
	s_waitcnt vmcnt(16)
	s_waitcnt vmcnt(0)
	ds_write2_b32 v31, v27, v54 offset1:66
	ds_write2_b32 v31, v55, v56 offset0:132 offset1:198
	ds_write2_b32 v37, v57, v58 offset0:8 offset1:74
	ds_write2_b32 v37, v59, v60 offset0:140 offset1:206
	ds_write2_b32 v38, v61, v62 offset0:16 offset1:82
	ds_write2_b32 v38, v63, v64 offset0:148 offset1:214
	ds_write2_b32 v39, v65, v66 offset0:24 offset1:90
	ds_write2_b32 v39, v67, v68 offset0:156 offset1:222
	ds_write2_b32 v40, v69, v70 offset0:32 offset1:98
	ds_write2_b32 v40, v71, v72 offset0:164 offset1:230
	ds_write2_b32 v41, v73, v74 offset0:40 offset1:106
	ds_write2_b32 v41, v75, v52 offset0:172 offset1:238
	ds_write2_b32 v42, v2, v3 offset0:48 offset1:114
	ds_write2_b32 v42, v4, v5 offset0:180 offset1:246
	ds_write2_b32 v43, v6, v7 offset0:56 offset1:122
	ds_write2_b32 v43, v44, v0 offset0:188 offset1:254
	s_waitcnt lgkmcnt(0)
	ds_read2_b32 v[4:5], v33 offset0:33 offset1:41
	ds_read2_b32 v[6:7], v33 offset1:8
	ds_read2_b32 v[44:45], v33 offset0:66 offset1:74
	ds_read2_b32 v[46:47], v33 offset0:99 offset1:107
	ds_read2_b32 v[48:49], v33 offset0:132 offset1:140
	ds_read2_b32 v[50:51], v33 offset0:165 offset1:173
	ds_read2_b32 v[52:53], v33 offset0:198 offset1:206
	ds_read2_b32 v[54:55], v33 offset0:231 offset1:239
	s_waitcnt lgkmcnt(6)
	v_cvt_pk_bf16_f32 v0, v6, v4
	v_or_b32_e32 v4, s26, v32
	v_lshl_add_u64 v[56:57], s[16:17], 1, v[14:15]
	v_lshlrev_b32_e32 v58, 11, v4
	v_mov_b32_e32 v59, v9
	s_waitcnt lgkmcnt(4)
	v_cvt_pk_bf16_f32 v1, v44, v46
	s_waitcnt lgkmcnt(2)
	v_cvt_pk_bf16_f32 v2, v48, v50
	s_waitcnt lgkmcnt(0)
	v_cvt_pk_bf16_f32 v3, v52, v54
	v_lshl_add_u64 v[58:59], v[56:57], 0, v[58:59]
	global_store_dwordx4 v[58:59], v[0:3], off nt
	v_or_b32_e32 v4, s26, v34
	v_lshlrev_b32_e32 v4, 11, v4
	v_cvt_pk_bf16_f32 v0, v7, v5
	v_cvt_pk_bf16_f32 v1, v45, v47
	v_cvt_pk_bf16_f32 v2, v49, v51
	v_cvt_pk_bf16_f32 v3, v53, v55
	ds_read2_b32 v[6:7], v33 offset0:49 offset1:57
	ds_read2_b32 v[44:45], v33 offset0:16 offset1:24
	ds_read2_b32 v[46:47], v33 offset0:82 offset1:90
	ds_read2_b32 v[48:49], v33 offset0:115 offset1:123
	ds_read2_b32 v[50:51], v33 offset0:148 offset1:156
	ds_read2_b32 v[52:53], v33 offset0:181 offset1:189
	ds_read2_b32 v[54:55], v33 offset0:214 offset1:222
	ds_read2_b32 v[58:59], v33 offset0:247 offset1:255
	v_mov_b32_e32 v5, v9
	v_lshl_add_u64 v[4:5], v[56:57], 0, v[4:5]
	global_store_dwordx4 v[4:5], v[0:3], off nt
	v_or_b32_e32 v4, s26, v35
	v_lshlrev_b32_e32 v4, 11, v4
	v_mov_b32_e32 v5, v9
	s_waitcnt lgkmcnt(6)
	v_cvt_pk_bf16_f32 v0, v44, v6
	s_waitcnt lgkmcnt(4)
	v_cvt_pk_bf16_f32 v1, v46, v48
	s_waitcnt lgkmcnt(2)
	v_cvt_pk_bf16_f32 v2, v50, v52
	s_waitcnt lgkmcnt(0)
	v_cvt_pk_bf16_f32 v3, v54, v58
	v_lshl_add_u64 v[4:5], v[56:57], 0, v[4:5]
	global_store_dwordx4 v[4:5], v[0:3], off nt
	v_or_b32_e32 v4, s26, v36
	v_lshlrev_b32_e32 v4, 11, v4
	v_mov_b32_e32 v5, v9
	v_cvt_pk_bf16_f32 v0, v45, v7
	v_cvt_pk_bf16_f32 v1, v47, v49
	v_cvt_pk_bf16_f32 v2, v51, v53
	v_cvt_pk_bf16_f32 v3, v55, v59
	v_lshl_add_u64 v[4:5], v[56:57], 0, v[4:5]
	global_store_dwordx4 v[4:5], v[0:3], off nt
	s_waitcnt lgkmcnt(0)
